# C-FIXREF loop: LDS-DMA addresses via per-wave SGPR bases (readfirstlane) + 32-bit lane offsets, no 64-bit VALU adds per step; on top of A DMA restructure and A VALU cleanup
# baseline (speedup 1.0000x reference)
; template <int TYPE, bool FIXREF>
; DI void attn_dense_unit(const Params& p, int layer, int head, int qb, char* lds, float bref) {
;     ...
;     const bf16_t* qp = Z + (size_t)q * ZP + ZC_QC + head * 64 + 8 * h;
;     float x[4][8]; float ss = 0.f;
; #pragma unroll
;     for (int d0 = 0; d0 < 4; ++d0) { unpack8(*(const u32x4*)(qp + d0 * 16), x[d0]);
; #pragma unroll
;       for (int j = 0; j < 8; ++j) ss += x[d0][j] * x[d0][j]; }
;     ss += __shfl_xor(ss, 32);
;     const float rs = rsqrtf(ss * (1.0f / 64.0f) + 1e-6f);
;     const float* gq = p.c_q_norm + layer * 64;
; #pragma unroll
;     for (int d0 = 0; d0 < 4; ++d0)
; #pragma unroll
;       for (int j = 0; j < 8; ++j) x[d0][j] *= rs * gq[d0 * 16 + 8 * h + j];
.LBB0_539:
	s_and_b64 vcc, exec, s[4:5]
	s_cbranch_vccz .LBB0_543
	v_mov_b32_e32 v98, v250
	v_mov_b64_e32 v[0:1], s[92:93]
	v_readfirstlane_b32 s4, v98
	s_ashr_i32 s4, s4, 6
	v_and_b32_e32 v100, 31, v98
	s_add_i32 s5, s4, s45
	v_lshl_or_b32 v148, s5, 5, v100
	v_bfe_u32 v99, v98, 5, 1
	v_mad_i64_i32 v[0:1], s[6:7], v148, s73, v[0:1]
	s_lshl_b32 s68, s44, 1
	v_lshl_add_u64 v[0:1], v[0:1], 0, s[68:69]
	v_lshlrev_b32_e32 v172, 4, v99
	v_lshl_add_u64 v[16:17], v[0:1], 0, v[172:173]
	s_mov_b64 s[6:7], 0x2e19e00
	v_lshl_add_u64 v[18:19], v[16:17], 0, s[6:7]
	global_load_dwordx4 v[62:65], v[18:19], off offset:64
	global_load_dwordx4 v[66:69], v[18:19], off offset:96
	v_lshlrev_b32_e32 v0, 7, v148
	s_mov_b32 s6, 0x2e19000
	v_and_b32_e32 v0, 0x1f80, v0
	v_mov_b32_e32 v1, v173
	v_add_co_u32_e32 v16, vcc, s6, v16
	s_ashr_i32 s6, s5, 1
	v_lshlrev_b32_e32 v172, 6, v99
	v_lshl_add_u64 v[0:1], s[90:91], 0, v[0:1]
	s_ashr_i32 s7, s6, 31
	v_lshl_add_u64 v[12:13], v[0:1], 0, v[172:173]
	v_addc_co_u32_e32 v17, vcc, 0, v17, vcc
	s_lshl_b64 s[6:7], s[6:7], 7
	global_load_dwordx4 v[0:3], v[12:13], off offset:48
	global_load_dwordx4 v[4:7], v[12:13], off offset:32
	global_load_dwordx4 v[8:11], v[12:13], off offset:16
	s_nop 0
	global_load_dwordx4 v[12:15], v[12:13], off
	s_add_u32 s6, s90, s6
	global_load_dwordx4 v[48:51], v[16:17], off offset:3584
	global_load_dwordx4 v[52:55], v[18:19], off offset:32
	s_addc_u32 s7, s91, s7
	global_load_dwordx4 v[16:19], v172, s[6:7] offset:48
	v_readlane_b32 s8, v255, 32
	v_lshlrev_b32_e32 v110, 5, v99
	v_readlane_b32 s9, v255, 33
	s_nop 4
	global_load_dwordx4 v[24:27], v110, s[8:9] offset:144
	global_load_dwordx4 v[32:35], v110, s[8:9] offset:128
	global_load_dwordx4 v[20:23], v110, s[8:9] offset:208
	global_load_dwordx4 v[28:31], v110, s[8:9] offset:192
	global_load_dwordx4 v[70:73], v110, s[8:9] offset:16
	global_load_dwordx4 v[74:77], v110, s[8:9]
	global_load_dwordx4 v[36:39], v172, s[6:7] offset:32
	global_load_dwordx4 v[40:43], v172, s[6:7] offset:16
	global_load_dwordx4 v[44:47], v172, s[6:7]
	s_lshl_b32 s5, s43, 1
	v_readlane_b32 s6, v252, 59
	v_readlane_b32 s7, v252, 60
	s_add_u32 s6, s6, s5
	s_addc_u32 s7, s7, 0
	s_lshl_b32 s4, s4, 10
	v_lshrrev_b32_e32 v101, 5, v98
	v_lshlrev_b32_e32 v150, 3, v99
	v_ashrrev_i32_e32 v149, 31, v148
	s_mov_b64 s[12:13], 0x30ea200
	s_mov_b64 s[14:15], 0x17618180
	s_mov_b64 s[16:17], 0x31da200
	s_mov_b64 s[18:19], 0x17618200
	s_mov_b64 s[34:35], 0x32ca200
	s_mov_b64 s[44:45], 0x33ba200
	s_mov_b64 s[46:47], 0x17618300
	s_waitcnt vmcnt(0)
	v_lshlrev_b32_e32 v58, 16, v65
	v_and_b32_e32 v59, 0xffff0000, v65
	v_lshlrev_b32_e32 v56, 16, v69
	v_and_b32_e32 v57, 0xffff0000, v69
	v_lshlrev_b32_e32 v78, 16, v64
	v_and_b32_e32 v79, 0xffff0000, v64
	v_lshlrev_b32_e32 v60, 16, v68
	v_and_b32_e32 v61, 0xffff0000, v68
	v_lshlrev_b32_e32 v80, 16, v63
	v_and_b32_e32 v81, 0xffff0000, v63
	v_lshlrev_b32_e32 v82, 16, v67
	v_and_b32_e32 v83, 0xffff0000, v67
	v_lshlrev_b32_e32 v84, 16, v62
	v_and_b32_e32 v85, 0xffff0000, v62
	v_lshlrev_b32_e32 v86, 16, v66
	v_and_b32_e32 v87, 0xffff0000, v66
	global_load_dwordx4 v[62:65], v110, s[8:9] offset:80
	global_load_dwordx4 v[66:69], v110, s[8:9] offset:64
	v_mov_b32_e32 v96, v1
	v_lshlrev_b32_e32 v130, 16, v48
	v_and_b32_e32 v131, 0xffff0000, v48
	v_lshlrev_b32_e32 v122, 16, v49
	v_and_b32_e32 v123, 0xffff0000, v49
	v_pk_mul_f32 v[48:49], v[130:131], v[130:131]
	v_mov_b32_e32 v116, v17
	v_pk_mul_f32 v[124:125], v[122:123], v[122:123]
	v_add_f32_e32 v17, v48, v49
	v_lshlrev_b32_e32 v118, 16, v50
	v_and_b32_e32 v119, 0xffff0000, v50
	v_add_f32_e32 v17, v124, v17
	v_mov_b32_e32 v97, v3
	v_mov_b32_e32 v1, v2
	v_mov_b32_e32 v2, v5
	v_mov_b32_e32 v3, v7
	v_mov_b32_e32 v5, v6
	v_mov_b32_e32 v6, v9
	v_mov_b32_e32 v7, v11
	v_mov_b32_e32 v9, v10
	v_mov_b32_e32 v10, v13
	v_mov_b32_e32 v11, v15
	v_mov_b32_e32 v13, v14
	v_lshlrev_b32_e32 v14, 16, v51
	v_and_b32_e32 v15, 0xffff0000, v51
	v_pk_mul_f32 v[50:51], v[118:119], v[118:119]
	v_add_f32_e32 v17, v125, v17
	v_add_f32_e32 v17, v50, v17
	v_pk_mul_f32 v[110:111], v[14:15], v[14:15]
	v_add_f32_e32 v17, v51, v17
	v_lshlrev_b32_e32 v132, 16, v52
	v_and_b32_e32 v133, 0xffff0000, v52
	v_add_f32_e32 v17, v110, v17
	v_lshlrev_b32_e32 v126, 16, v53
	v_and_b32_e32 v127, 0xffff0000, v53
	v_pk_mul_f32 v[52:53], v[132:133], v[132:133]
	v_add_f32_e32 v17, v111, v17
	v_add_f32_e32 v17, v52, v17
	v_pk_mul_f32 v[128:129], v[126:127], v[126:127]
	v_add_f32_e32 v17, v53, v17
	v_lshlrev_b32_e32 v120, 16, v54
	v_and_b32_e32 v121, 0xffff0000, v54
	v_add_f32_e32 v17, v128, v17
	v_lshlrev_b32_e32 v112, 16, v55
	v_and_b32_e32 v113, 0xffff0000, v55
	v_pk_mul_f32 v[54:55], v[120:121], v[120:121]
	v_add_f32_e32 v17, v129, v17
	v_add_f32_e32 v17, v54, v17
	v_pk_mul_f32 v[114:115], v[112:113], v[112:113]
	v_add_f32_e32 v17, v55, v17
	v_add_f32_e32 v17, v114, v17
	v_pk_mul_f32 v[106:107], v[84:85], v[84:85]
	v_add_f32_e32 v17, v115, v17
	v_add_f32_e32 v17, v106, v17
	v_pk_mul_f32 v[102:103], v[80:81], v[80:81]
	v_add_f32_e32 v17, v107, v17
	v_add_f32_e32 v17, v102, v17
	v_pk_mul_f32 v[92:93], v[78:79], v[78:79]
	v_add_f32_e32 v17, v103, v17
	v_add_f32_e32 v17, v92, v17
	v_pk_mul_f32 v[88:89], v[58:59], v[58:59]
	v_add_f32_e32 v17, v93, v17
	v_add_f32_e32 v17, v88, v17
	v_pk_mul_f32 v[108:109], v[86:87], v[86:87]
	v_add_f32_e32 v17, v89, v17
	v_add_f32_e32 v17, v108, v17
	v_pk_mul_f32 v[104:105], v[82:83], v[82:83]
	v_add_f32_e32 v17, v109, v17
	v_add_f32_e32 v17, v104, v17
	v_pk_mul_f32 v[94:95], v[60:61], v[60:61]
	v_add_f32_e32 v17, v105, v17
	v_add_f32_e32 v17, v94, v17
	v_pk_mul_f32 v[90:91], v[56:57], v[56:57]
	v_add_f32_e32 v17, v95, v17
	v_add_f32_e32 v17, v90, v17
	v_add_f32_e32 v48, v91, v17
	ds_bpermute_b32 v49, v199, v48
	v_mov_b32_e32 v17, v18
	v_mov_b32_e32 v18, v37
	v_mov_b32_e32 v37, v38
	v_mov_b32_e32 v117, v19
	s_waitcnt lgkmcnt(0)
; template <int TYPE, bool FIXREF>
; DI void attn_dense_unit(const Params& p, int layer, int head, int qb, char* lds, float bref) {
;     ...
;     ss += __shfl_xor(ss, 32);
;     const float rs = rsqrtf(ss * (1.0f / 64.0f) + 1e-6f);
;     const float* gq = p.c_q_norm + layer * 64;
; #pragma unroll
;     for (int d0 = 0; d0 < 4; ++d0)
; #pragma unroll
;       for (int j = 0; j < 8; ++j) x[d0][j] *= rs * gq[d0 * 16 + 8 * h + j];
;     rope_pair8(x[0], x[1], CS + (size_t)(q >> 6) * 16 + 8 * h);
;     rope_pair8(x[2], x[3], CS + (size_t)(q & 63) * 16 + 8 * h);
;     const float sc = 0.125f * LOG2E;
; #pragma unroll
;     for (int d0 = 0; d0 < 4; ++d0) qf[d0] = pack8(x[d0][0] * sc, x[d0][1] * sc, x[d0][2] * sc, x[d0][3] * sc, x[d0][4] * sc, x[d0][5] * sc, x[d0][6] * sc, x[d0][7] * sc);
;     ...
;   const int srow = tid >> 3, sch = (tid & 7) ^ ((srow >> 1) & 7);
;   const bf16_t* gk = Kn + (size_t)srow * ldk + sch * 8;
;   const bf16_t* gv = VT + (size_t)srow * S + sch * 8;
;   const int rrow = tid >> 2, rch = (tid & 3) ^ ((rrow >> 2) & 3);
;   const bf16_t* gr = Z + ZC_KR + (size_t)rrow * ZP + rch * 8;
;   char* wbase = lds + wid * 1024;
	v_add_f32_e32 v38, v48, v49
	v_fmamk_f32 v38, v38, 0x3c800000, v197
	v_mov_b32_e32 v19, v39
	v_mul_f32_e32 v39, 0x4b800000, v38
	v_cmp_gt_f32_e32 vcc, s33, v38
	s_mov_b64 s[8:9], 0x100
	s_nop 0
	v_cndmask_b32_e32 v38, v38, v39, vcc
	v_rsq_f32_e32 v48, v38
	v_mov_b32_e32 v38, v41
	v_mov_b32_e32 v41, v42
	v_mov_b32_e32 v39, v43
	v_mul_f32_e32 v42, 0x45800000, v48
	v_cndmask_b32_e32 v42, v48, v42, vcc
	s_waitcnt vmcnt(1)
	v_pk_mul_f32 v[62:63], v[62:63], v[42:43] op_sel_hi:[1,0]
	v_pk_mul_f32 v[52:53], v[70:71], v[42:43] op_sel_hi:[1,0]
	v_pk_mul_f32 v[62:63], v[62:63], v[120:121]
	v_pk_mul_f32 v[26:27], v[26:27], v[42:43] op_sel_hi:[1,0]
	v_pk_mul_f32 v[52:53], v[52:53], v[118:119]
	v_pk_mul_f32 v[54:55], v[72:73], v[42:43] op_sel_hi:[1,0]
	v_pk_mul_f32 v[26:27], v[26:27], v[58:59]
	v_pk_mul_f32 v[28:29], v[28:29], v[42:43] op_sel_hi:[1,0]
	v_pk_mul_f32 v[58:59], v[36:37], v[62:63]
	v_pk_mul_f32 v[14:15], v[54:55], v[14:15]
	s_waitcnt vmcnt(0)
	v_pk_mul_f32 v[54:55], v[66:67], v[42:43] op_sel_hi:[1,0]
	v_pk_mul_f32 v[66:67], v[68:69], v[42:43] op_sel_hi:[1,0]
	v_pk_mul_f32 v[32:33], v[32:33], v[42:43] op_sel_hi:[1,0]
	v_pk_mul_f32 v[28:29], v[28:29], v[86:87]
	v_pk_mul_f32 v[30:31], v[30:31], v[42:43] op_sel_hi:[1,0]
	v_pk_fma_f32 v[58:59], v[18:19], v[52:53], v[58:59]
	v_pk_mul_f32 v[18:19], v[18:19], v[62:63]
	v_pk_mul_f32 v[50:51], v[76:77], v[42:43] op_sel_hi:[1,0]
	v_pk_mul_f32 v[66:67], v[66:67], v[126:127]
	v_pk_mul_f32 v[64:65], v[64:65], v[42:43] op_sel_hi:[1,0]
	v_pk_mul_f32 v[32:33], v[32:33], v[84:85]
	v_pk_mul_f32 v[34:35], v[34:35], v[42:43] op_sel_hi:[1,0]
	v_pk_mul_f32 v[30:31], v[30:31], v[82:83]
	v_pk_mul_f32 v[22:23], v[22:23], v[42:43] op_sel_hi:[1,0]
	v_pk_mul_f32 v[68:69], v[28:29], v[12:13]
	v_pk_fma_f32 v[18:19], v[36:37], v[52:53], v[18:19] neg_lo:[0,0,1] neg_hi:[0,0,1]
	v_pk_mul_f32 v[50:51], v[50:51], v[122:123]
	v_pk_mul_f32 v[64:65], v[64:65], v[112:113]
	v_pk_mul_f32 v[34:35], v[34:35], v[80:81]
	v_pk_mul_f32 v[20:21], v[20:21], v[42:43] op_sel_hi:[1,0]
	v_pk_mul_f32 v[22:23], v[22:23], v[56:57]
	v_pk_mul_f32 v[56:57], v[40:41], v[66:67]
	v_pk_fma_f32 v[102:103], v[32:33], v[10:11], v[68:69]
	v_pk_mul_f32 v[68:69], v[30:31], v[8:9]
	v_pk_mul_f32 v[18:19], v[18:19], s[78:79] op_sel_hi:[1,0]
	v_pk_mul_f32 v[48:49], v[74:75], v[42:43] op_sel_hi:[1,0]
	v_pk_mul_f32 v[54:55], v[54:55], v[132:133]
	v_pk_mul_f32 v[24:25], v[24:25], v[42:43] op_sel_hi:[1,0]
	v_pk_mul_f32 v[20:21], v[20:21], v[60:61]
	v_mov_b32_e32 v42, v45
	v_mov_b32_e32 v45, v46
	v_pk_fma_f32 v[56:57], v[38:39], v[50:51], v[56:57]
	v_pk_mul_f32 v[60:61], v[16:17], v[64:65]
	v_pk_fma_f32 v[104:105], v[34:35], v[6:7], v[68:69]
	v_pk_mul_f32 v[36:37], v[116:117], v[64:65]
	v_cvt_pk_bf16_f32 v134, v18, v19
	v_pk_mul_f32 v[18:19], v[58:59], s[78:79] op_sel_hi:[1,0]
	v_pk_mul_f32 v[6:7], v[30:31], v[6:7]
	v_pk_mul_f32 v[48:49], v[48:49], v[130:131]
	v_mov_b32_e32 v43, v47
	v_pk_mul_f32 v[46:47], v[44:45], v[54:55]
	v_pk_fma_f32 v[60:61], v[116:117], v[14:15], v[60:61]
	v_pk_fma_f32 v[14:15], v[16:17], v[14:15], v[36:37] neg_lo:[0,0,1] neg_hi:[0,0,1]
	v_pk_mul_f32 v[16:17], v[56:57], s[78:79] op_sel_hi:[1,0]
	v_cvt_pk_bf16_f32 v130, v18, v19
	v_pk_mul_f32 v[10:11], v[28:29], v[10:11]
	v_pk_fma_f32 v[6:7], v[34:35], v[8:9], v[6:7] neg_lo:[0,0,1] neg_hi:[0,0,1]
	v_ashrrev_i32_e32 v18, 3, v98
	v_lshrrev_b32_e32 v28, 4, v98
	v_pk_mul_f32 v[24:25], v[24:25], v[78:79]
	v_pk_fma_f32 v[46:47], v[42:43], v[48:49], v[46:47]
	v_pk_mul_f32 v[68:69], v[20:21], v[4:5]
	v_pk_mul_f32 v[14:15], v[14:15], s[78:79] op_sel_hi:[1,0]
	v_cvt_pk_bf16_f32 v129, v16, v17
	v_pk_mul_f32 v[16:17], v[6:7], s[78:79] op_sel_hi:[1,0]
	v_xor_b32_e32 v6, v28, v98
	v_ashrrev_i32_e32 v19, 31, v18
	v_pk_fma_f32 v[106:107], v[24:25], v[2:3], v[68:69]
	v_cvt_pk_bf16_f32 v135, v14, v15
	v_pk_mul_f32 v[14:15], v[46:47], s[78:79] op_sel_hi:[1,0]
	v_pk_fma_f32 v[10:11], v[32:33], v[12:13], v[10:11] neg_lo:[0,0,1] neg_hi:[0,0,1]
	v_pk_mul_f32 v[2:3], v[20:21], v[2:3]
	v_lshlrev_b64 v[20:21], 15, v[18:19]
	v_lshlrev_b32_e32 v6, 4, v6
	v_cvt_pk_bf16_f32 v128, v14, v15
	v_pk_mul_f32 v[14:15], v[10:11], s[78:79] op_sel_hi:[1,0]
	v_pk_fma_f32 v[10:11], v[24:25], v[4:5], v[2:3] neg_lo:[0,0,1] neg_hi:[0,0,1]
	v_lshl_add_u64 v[2:3], s[6:7], 0, v[20:21]
	v_and_b32_e32 v172, 0x70, v6
	v_lshl_add_u64 v[152:153], v[2:3], 0, v[172:173]
	v_lshlrev_b32_e32 v3, 1, v98
	v_lshrrev_b32_e32 v6, 1, v98
	v_mov_b64_e32 v[4:5], s[0:1]
	v_and_b32_e32 v2, 19, v98
	v_and_b32_e32 v3, 8, v3
	v_and_b32_e32 v6, 4, v6
	v_mad_i64_i32 v[4:5], s[0:1], v18, s73, v[4:5]
	v_or3_b32 v2, v3, v2, v6
	v_lshrrev_b32_e32 v19, 1, v2
	s_add_i32 s0, s4, 0
	v_lshlrev_b32_e32 v29, 7, v2
	v_bitop3_b32 v2, v19, v99, 7 bitop3:0x6c
	v_lshl_add_u64 v[154:155], v[4:5], 0, v[172:173]
	s_mov_b32 m0, s0
	s_add_i32 s1, s0, 0x2000
	s_mov_b64 s[4:5], 0xf0000
	v_lshl_or_b32 v207, v2, 4, v29
	global_load_lds_dwordx4 v[154:155], off
	s_mov_b32 m0, s1
	v_lshl_add_u64 v[2:3], v[154:155], 0, s[4:5]
	s_add_i32 s4, s0, 0x5000
	global_load_lds_dwordx4 v[152:153], off
	s_mov_b32 m0, s4
	s_add_i32 s5, s0, 0x7000
	global_load_lds_dwordx4 v[2:3], off
	v_lshl_add_u64 v[2:3], v[152:153], 0, s[76:77]
	s_mov_b32 m0, s5
	s_mov_b64 s[6:7], 0x1e0000
	global_load_lds_dwordx4 v[2:3], off
	v_lshl_add_u64 v[2:3], v[154:155], 0, s[6:7]
	s_add_i32 s6, s0, 0xa000
	s_mov_b32 m0, s6
	s_add_i32 s7, s0, 0xc000
	global_load_lds_dwordx4 v[2:3], off
	v_lshl_add_u64 v[2:3], v[152:153], 0, s[8:9]
	s_mov_b32 m0, s7
	v_add_u32_e32 v201, 0, v207
	global_load_lds_dwordx4 v[2:3], off
	s_waitcnt vmcnt(2)
	s_waitcnt lgkmcnt(0)
	s_barrier
; #define QKR(d0, K0, K1, SOFF) do { if ((d0) < 4) { K0 = *(const bf16x8*)(lds + (SOFF) + koff[(d0) & 3]); K1 = *(const bf16x8*)(lds + (SOFF) + 32 * 128 + koff[(d0) & 3]); } \
;     else if ((d0) < NQK) { K0 = *(const bf16x8*)(lds + (SOFF) + roff[(d0) & 1]); K1 = *(const bf16x8*)(lds + (SOFF) + 32 * 64 + roff[(d0) & 1]); } } while (0)
; #define QKM(N0, N1, d0, K0, K1) do { if ((d0) == 0) { N0 = MFMA(K0, qf[0], negm); N1 = MFMA(K1, qf[0], negm); } \
;     else if ((d0) < NQK) { N0 = MFMA(K0, qf[(d0) < NQK ? (d0) : 0], N0); N1 = MFMA(K1, qf[(d0) < NQK ? (d0) : 0], N1); } } while (0)
; template <int TYPE, bool FIXREF>
; DI void attn_dense_unit(const Params& p, int layer, int head, int qb, char* lds, float bref) {
;     ...
;   float m_run = 0.f, lsum = 0.f, ls0 = 0.f, ls1 = 0.f, ls2 = 0.f; f32x16 o0, o1, negm, la;
; #pragma unroll
;   for (int i = 0; i < 16; ++i) { o0[i] = 0.f; o1[i] = 0.f; negm[i] = 0.f; la[i] = 0.f; }
;   const bf16x8 ones = {0x3F80, 0x3F80, 0x3F80, 0x3F80, 0x3F80, 0x3F80, 0x3F80, 0x3F80};
;   const int rK = (r & ~12) | ((r & 4) << 1) | ((r & 8) >> 1);
;   const int ksw = (rK >> 1) & 7, rsw = (rK >> 2) & 3, vsw = (r >> 1) & 7;
;   int koff[4], roff[2], voff[4];
; #pragma unroll
;   for (int d0 = 0; d0 < 4; ++d0) { koff[d0] = rK * 128 + (((2 * d0 + h) ^ ksw) << 4); voff[d0] = 8192 + r * 128 + (((2 * d0 + h) ^ vsw) << 4); }
; #pragma unroll
;   for (int d0 = 0; d0 < 2; ++d0) roff[d0] = 16384 + rK * 64 + (((2 * d0 + h) ^ rsw) << 4);
;     ...
;   if (FIXREF) { m_run = bref;
; #pragma unroll
;     for (int i = 0; i < 16; ++i) negm[i] = -bref; }
;   { bf16x8 ka0, ka1;
; #pragma unroll
;     for (int d0 = 0; d0 < NQK; ++d0) { QKR(d0, ka0, ka1, R0); QKM(sA0, sA1, d0, ka0, ka1); } }
	ds_read_b128 v[2:5], v201 offset:4096
	ds_read_b128 v[6:9], v201
	v_pk_mul_f32 v[42:43], v[42:43], v[54:55]
	v_pk_mul_f32 v[38:39], v[38:39], v[66:67]
	v_pk_fma_f32 v[42:43], v[44:45], v[48:49], v[42:43] neg_lo:[0,0,1] neg_hi:[0,0,1]
	v_pk_fma_f32 v[38:39], v[40:41], v[50:51], v[38:39] neg_lo:[0,0,1] neg_hi:[0,0,1]
	v_pk_mul_f32 v[42:43], v[42:43], s[78:79] op_sel_hi:[1,0]
	v_pk_mul_f32 v[38:39], v[38:39], s[78:79] op_sel_hi:[1,0]
	v_xor_b32_e32 v48, 0x80000000, v163
	v_cvt_pk_bf16_f32 v132, v42, v43
	v_cvt_pk_bf16_f32 v133, v38, v39
	v_pk_mul_f32 v[36:37], v[60:61], s[78:79] op_sel_hi:[1,0]
	v_mov_b32_e32 v49, v48
	v_mov_b32_e32 v50, v48
	v_mov_b32_e32 v51, v48
	v_mov_b32_e32 v52, v48
	v_mov_b32_e32 v53, v48
	v_mov_b32_e32 v54, v48
	v_mov_b32_e32 v55, v48
	v_mov_b32_e32 v56, v48
	v_mov_b32_e32 v57, v48
	v_mov_b32_e32 v58, v48
	v_mov_b32_e32 v59, v48
	v_mov_b32_e32 v60, v48
	v_mov_b32_e32 v61, v48
	v_mov_b32_e32 v62, v48
	v_mov_b32_e32 v63, v48
	v_pk_mul_f32 v[68:69], v[22:23], v[0:1]
	v_pk_mul_f32 v[24:25], v[10:11], s[78:79] op_sel_hi:[1,0]
	s_waitcnt lgkmcnt(0)
	v_mfma_f32_32x32x16_bf16 v[80:95], v[6:9], v[132:135], v[48:63]
	v_or_b32_e32 v6, 2, v99
	v_bitop3_b32 v6, v19, v6, 7 bitop3:0x6c
	v_lshl_or_b32 v208, v6, 4, v29
	v_fma_f32 v108, v26, v96, v68
	v_fma_f32 v109, v27, v97, v69
	v_add_u32_e32 v202, 0, v208
	ds_read_b128 v[6:9], v202 offset:4096
	ds_read_b128 v[10:13], v202
	v_cvt_pk_bf16_f32 v131, v36, v37
	v_mfma_f32_32x32x16_bf16 v[64:79], v[2:5], v[132:135], v[48:63]
	v_mul_f32_e64 v2, v22, v96
	v_mul_f32_e64 v3, v23, v97
	v_mul_f32_e64 v4, v102, s78
	v_mul_f32_e64 v5, v103, s78
	v_fma_f32 v0, v26, v0, -v2
	v_fma_f32 v1, v27, v1, -v3
	v_cvt_pk_bf16_f32 v140, v14, v15
	v_pk_mul_f32 v[0:1], v[0:1], s[78:79] op_sel_hi:[1,0]
	v_cvt_pk_bf16_f32 v141, v16, v17
	v_cvt_pk_bf16_f32 v143, v0, v1
	v_or_b32_e32 v0, 4, v99
	s_waitcnt lgkmcnt(0)
	v_mfma_f32_32x32x16_bf16 v[80:95], v[10:13], v[128:131], v[80:95]
	v_bitop3_b32 v0, v19, v0, 7 bitop3:0x6c
	v_lshl_or_b32 v209, v0, 4, v29
	v_add_u32_e32 v204, 0, v209
	ds_read_b128 v[0:3], v204 offset:4096
	ds_read_b128 v[10:13], v204
	v_cvt_pk_bf16_f32 v142, v24, v25
	v_cvt_pk_bf16_f32 v136, v4, v5
	v_or_b32_e32 v4, 6, v99
	v_mfma_f32_32x32x16_bf16 v[64:79], v[6:9], v[128:131], v[64:79]
	v_bitop3_b32 v4, v19, v4, 7 bitop3:0x6c
	v_lshl_or_b32 v210, v4, 4, v29
	v_mul_f32_e64 v6, v104, s78
	v_mul_f32_e64 v7, v105, s78
	v_mul_f32_e64 v8, v106, s78
	v_mul_f32_e64 v9, v107, s78
	v_add_u32_e32 v203, 0, v210
	v_cvt_pk_bf16_f32 v137, v6, v7
	v_cvt_pk_bf16_f32 v138, v8, v9
	s_waitcnt lgkmcnt(0)
	v_mfma_f32_32x32x16_bf16 v[80:95], v[10:13], v[140:143], v[80:95]
	ds_read_b128 v[4:7], v203 offset:4096
	ds_read_b128 v[8:11], v203
	v_mul_f32_e64 v14, v108, s78
	v_mul_f32_e64 v15, v109, s78
	s_add_i32 s8, s0, 0x11000
	v_cvt_pk_bf16_f32 v139, v14, v15
	v_bfe_u32 v12, v98, 1, 3
	s_add_u32 s10, s92, s42
	s_addc_u32 s11, s93, 0
	v_mfma_f32_32x32x16_bf16 v[64:79], v[0:3], v[140:143], v[64:79]
	v_lshlrev_b32_e32 v0, 7, v100
	v_bitop3_b32 v2, v101, v12, 1 bitop3:0x6c
	v_bitop3_b32 v3, v99, v12, 2 bitop3:0x36
	v_or_b32_e32 v1, 0x2000, v0
	v_lshlrev_b32_e32 v2, 4, v2
	v_lshlrev_b32_e32 v3, 4, v3
	v_lshl_add_u64 v[158:159], s[10:11], 0, v[20:21]
	s_waitcnt lgkmcnt(0)
	v_mfma_f32_32x32x16_bf16 v[80:95], v[8:11], v[136:139], v[80:95]
	v_bitop3_b32 v8, v99, v12, 4 bitop3:0x36
	v_bitop3_b32 v9, v99, v12, 6 bitop3:0x36
	v_lshlrev_b32_e32 v8, 4, v8
	v_lshlrev_b32_e32 v9, 4, v9
	s_add_u32 s10, s92, s31
	v_or_b32_e32 v211, v2, v1
	v_or_b32_e32 v212, v3, v1
	v_mfma_f32_32x32x16_bf16 v[64:79], v[4:7], v[136:139], v[64:79]
	v_or_b32_e32 v2, v2, v0
	v_or_b32_e32 v3, v3, v0
	v_or_b32_e32 v4, v8, v0
	v_or_b32_e32 v5, v9, v0
	v_bitop3_b32 v0, v28, 7, v98 bitop3:0x48
	s_addc_u32 s11, s93, 0
	v_or_b32_e32 v213, v8, v1
	v_or_b32_e32 v214, v9, v1
	v_lshlrev_b32_e32 v172, 4, v0
	v_mov_b64_e32 v[0:1], s[10:11]
	v_mov_b32_e32 v32, 0
	v_mad_i64_i32 v[160:161], s[10:11], v18, s73, v[0:1]
	s_mov_b32 s9, -4
	v_add_u32_e32 v206, 0, v2
	v_add_u32_e32 v205, 0, v3
	v_add_u32_e32 v200, 0, v4
	v_add_u32_e32 v151, 0, v5
	v_mov_b32_e32 v33, v32
	v_mov_b32_e32 v34, v32
	v_mov_b32_e32 v35, v32
	v_mov_b32_e32 v36, v32
	v_mov_b32_e32 v37, v32
	v_mov_b32_e32 v38, v32
	v_mov_b32_e32 v39, v32
	v_mov_b32_e32 v40, v32
	v_mov_b32_e32 v41, v32
	v_mov_b32_e32 v42, v32
	v_mov_b32_e32 v43, v32
	v_mov_b32_e32 v44, v32
	v_mov_b32_e32 v45, v32
	v_mov_b32_e32 v46, v32
	v_mov_b32_e32 v47, v32
	v_mov_b32_e32 v16, v32
	v_mov_b32_e32 v17, v32
	v_mov_b32_e32 v18, v32
	v_mov_b32_e32 v19, v32
	v_mov_b32_e32 v20, v32
	v_mov_b32_e32 v21, v32
	v_mov_b32_e32 v22, v32
	v_mov_b32_e32 v23, v32
	v_mov_b32_e32 v24, v32
	v_mov_b32_e32 v25, v32
	v_mov_b32_e32 v26, v32
	v_mov_b32_e32 v27, v32
	v_mov_b32_e32 v28, v32
	v_mov_b32_e32 v29, v32
	v_mov_b32_e32 v30, v32
	v_mov_b32_e32 v31, v32
	v_mov_b32_e32 v0, v32
	v_mov_b32_e32 v1, v32
	v_mov_b32_e32 v2, v32
	v_mov_b32_e32 v3, v32
	v_mov_b32_e32 v4, v32
	v_mov_b32_e32 v5, v32
	v_mov_b32_e32 v6, v32
	v_mov_b32_e32 v7, v32
	v_mov_b32_e32 v8, v32
	v_mov_b32_e32 v9, v32
	v_mov_b32_e32 v10, v32
	v_mov_b32_e32 v11, v32
	v_mov_b32_e32 v12, v32
	v_mov_b32_e32 v13, v32
	v_mov_b32_e32 v14, v32
	v_mov_b32_e32 v15, v32
	v_mov_b32_e32 v156, v32
	v_mov_b32_e32 v157, v32
	v_mov_b32_e32 v162, v32
	v_mov_b32_e32 v163, v32
	s_mov_b64 s[42:43], 0x17618280
	v_readfirstlane_b32 vcc_lo, v160
	v_readfirstlane_b32 vcc_hi, v161
	s_nop 3
	s_sub_u32 vcc_lo, vcc_lo, 0x1000
	s_subb_u32 vcc_hi, vcc_hi, 0
	v_add_u32_e32 v244, v160, v172
	v_subrev_u32_e32 v244, vcc_lo, v244
	s_add_u32 s12, s12, vcc_lo
	s_addc_u32 s13, s13, vcc_hi
	s_add_u32 s16, s16, vcc_lo
	s_addc_u32 s17, s17, vcc_hi
	s_add_u32 s34, s34, vcc_lo
	s_addc_u32 s35, s35, vcc_hi
	s_add_u32 s44, s44, vcc_lo
	s_addc_u32 s45, s45, vcc_hi
	v_readfirstlane_b32 vcc_lo, v158
	v_readfirstlane_b32 vcc_hi, v159
	s_nop 3
	s_sub_u32 vcc_lo, vcc_lo, 0x1000
	s_subb_u32 vcc_hi, vcc_hi, 0
	v_add_u32_e32 v245, v158, v172
	v_subrev_u32_e32 v245, vcc_lo, v245
	s_add_u32 s14, s14, vcc_lo
	s_addc_u32 s15, s15, vcc_hi
	s_add_u32 s18, s18, vcc_lo
	s_addc_u32 s19, s19, vcc_hi
	s_add_u32 s42, s42, vcc_lo
	s_addc_u32 s43, s43, vcc_hi
	s_add_u32 s46, s46, vcc_lo
	s_addc_u32 s47, s47, vcc_hi
.LBB0_541:
	s_add_i32 s10, s0, 0xf000
	s_mov_b32 m0, s10
	s_nop 0
	global_load_lds_dwordx4 v244, s[12:13]
	s_mov_b32 m0, s8
	s_nop 0
	global_load_lds_dwordx4 v245, s[14:15]
	ds_read_b128 v[96:99], v201 offset:20480
	ds_read_b128 v[144:147], v201 offset:24576
	ds_read_b128 v[100:103], v202 offset:20480
	ds_read_b128 v[168:171], v202 offset:24576
	v_exp_f32_e32 v180, v80
	v_exp_f32_e32 v181, v81
	v_exp_f32_e32 v182, v82
	v_exp_f32_e32 v183, v83
	s_waitcnt lgkmcnt(0)
	v_mfma_f32_32x32x16_bf16 v[112:127], v[96:99], v[132:135], v[48:63]
	ds_read_b128 v[80:83], v204 offset:20480
	ds_read_b128 v[174:177], v204 offset:24576
	v_exp_f32_e32 v84, v84
	v_exp_f32_e32 v85, v85
	v_exp_f32_e32 v86, v86
	v_exp_f32_e32 v87, v87
	v_mfma_f32_32x32x16_bf16 v[112:127], v[100:103], v[128:131], v[112:127]
	v_cvt_pk_bf16_f32 v180, v180, v181
	v_cvt_pk_bf16_f32 v181, v182, v183
	v_cvt_pk_bf16_f32 v182, v84, v85
	v_cvt_pk_bf16_f32 v183, v86, v87
	v_mfma_f32_32x32x16_bf16 v[96:111], v[144:147], v[132:135], v[48:63]
	ds_read_b128 v[84:87], v203 offset:20480
	ds_read_b128 v[144:147], v203 offset:24576
	s_waitcnt lgkmcnt(0)
	v_mfma_f32_32x32x16_bf16 v[112:127], v[80:83], v[140:143], v[112:127]
	v_exp_f32_e32 v80, v88
	v_exp_f32_e32 v81, v89
	v_exp_f32_e32 v82, v90
	v_exp_f32_e32 v83, v91
	v_mfma_f32_32x32x16_bf16 v[112:127], v[84:87], v[136:139], v[112:127]
	v_exp_f32_e32 v84, v92
	v_exp_f32_e32 v85, v93
	v_exp_f32_e32 v86, v94
	v_exp_f32_e32 v87, v95
	v_mfma_f32_32x32x16_bf16 v[96:111], v[168:171], v[128:131], v[96:111]
	v_cvt_pk_bf16_f32 v168, v80, v81
	v_cvt_pk_bf16_f32 v169, v82, v83
	v_cvt_pk_bf16_f32 v170, v84, v85
	v_cvt_pk_bf16_f32 v171, v86, v87
	ds_read_b128 v[80:83], v206 offset:8192
	ds_read_b128 v[84:87], v206 offset:12288
	v_mfma_f32_32x32x16_bf16 v[96:111], v[174:177], v[140:143], v[96:111]
	s_waitcnt lgkmcnt(0)
	v_mfma_f32_32x32x16_bf16 v[0:15], v[84:87], v[180:183], v[0:15]
	ds_read_b128 v[88:91], v205 offset:8192
	ds_read_b128 v[92:95], v205 offset:12288
	v_exp_f32_e32 v217, v64
	v_exp_f32_e32 v218, v65
	v_exp_f32_e32 v219, v66
	v_exp_f32_e32 v216, v67
	v_exp_f32_e32 v221, v68
	v_exp_f32_e32 v222, v69
	v_mfma_f32_32x32x16_bf16 v[16:31], v[80:83], v[180:183], v[16:31]
	v_exp_f32_e32 v223, v70
	v_exp_f32_e32 v220, v71
	v_cvt_pk_bf16_f32 v64, v217, v218
	v_cvt_pk_bf16_f32 v65, v219, v216
	v_cvt_pk_bf16_f32 v66, v221, v222
	v_cvt_pk_bf16_f32 v67, v223, v220
	s_waitcnt lgkmcnt(0)
	v_mfma_f32_32x32x16_bf16 v[0:15], v[92:95], v[168:171], v[0:15]
	ds_read_b128 v[68:71], v200 offset:8192
	ds_read_b128 v[174:177], v200 offset:12288
	v_exp_f32_e32 v225, v72
	v_exp_f32_e32 v226, v73
	v_exp_f32_e32 v227, v74
	v_exp_f32_e32 v224, v75
	v_exp_f32_e32 v229, v76
	v_exp_f32_e32 v230, v77
	v_mfma_f32_32x32x16_bf16 v[16:31], v[88:91], v[168:171], v[16:31]
	v_exp_f32_e32 v231, v78
	v_exp_f32_e32 v228, v79
	v_cvt_pk_bf16_f32 v72, v225, v226
	v_cvt_pk_bf16_f32 v73, v227, v224
	v_cvt_pk_bf16_f32 v74, v229, v230
	v_cvt_pk_bf16_f32 v75, v231, v228
	v_mfma_f32_32x32x16_bf16 v[96:111], v[144:147], v[136:139], v[96:111]
	s_waitcnt lgkmcnt(0)
	v_mfma_f32_32x32x16_bf16 v[16:31], v[68:71], v[64:67], v[16:31]
	ds_read_b128 v[76:79], v151 offset:8192
	ds_read_b128 v[184:187], v151 offset:12288
	s_waitcnt lgkmcnt(0)
	v_mfma_f32_32x32x16_bf16 v[16:31], v[76:79], v[72:75], v[16:31]
	s_waitcnt vmcnt(2)
	s_mov_b32 m0, s0
	s_waitcnt lgkmcnt(0)
	s_barrier
	global_load_lds_dwordx4 v244, s[16:17]
	s_mov_b32 m0, s1
	s_nop 0
	global_load_lds_dwordx4 v245, s[18:19]
	ds_read_b128 v[68:71], v201 offset:40960
	ds_read_b128 v[188:191], v201 offset:45056
	v_mfma_f32_32x32x16_bf16 v[0:15], v[174:177], v[64:67], v[0:15]
	v_mov_b64_e32 v[146:147], s[38:39]
	v_mov_b64_e32 v[144:145], s[36:37]
	ds_read_b128 v[64:67], v202 offset:40960
	ds_read_b128 v[174:177], v202 offset:45056
	v_exp_f32_e32 v192, v112
	v_exp_f32_e32 v193, v113
	v_exp_f32_e32 v194, v114
	v_exp_f32_e32 v195, v115
	s_waitcnt lgkmcnt(0)
	v_mfma_f32_32x32x16_bf16 v[80:95], v[68:71], v[132:135], v[48:63]
	v_mfma_f32_32x32x16_bf16 v[32:47], v[144:147], v[180:183], v[32:47]
	v_mfma_f32_32x32x16_bf16 v[0:15], v[184:187], v[72:75], v[0:15]
	v_mfma_f32_32x32x16_bf16 v[80:95], v[64:67], v[128:131], v[80:95]
	ds_read_b128 v[112:115], v204 offset:40960
	ds_read_b128 v[180:183], v204 offset:45056
	v_exp_f32_e32 v116, v116
	v_exp_f32_e32 v117, v117
	v_exp_f32_e32 v118, v118
	v_exp_f32_e32 v119, v119
	v_cvt_pk_bf16_f32 v192, v192, v193
	v_cvt_pk_bf16_f32 v193, v194, v195
	v_mfma_f32_32x32x16_bf16 v[64:79], v[188:191], v[132:135], v[48:63]
	v_cvt_pk_bf16_f32 v194, v116, v117
	v_cvt_pk_bf16_f32 v195, v118, v119
	s_waitcnt lgkmcnt(0)
	v_mfma_f32_32x32x16_bf16 v[80:95], v[112:115], v[140:143], v[80:95]
	ds_read_b128 v[112:115], v203 offset:40960
	ds_read_b128 v[116:119], v203 offset:45056
	v_exp_f32_e32 v120, v120
	v_exp_f32_e32 v121, v121
	v_exp_f32_e32 v122, v122
	v_exp_f32_e32 v123, v123
	v_mfma_f32_32x32x16_bf16 v[32:47], v[144:147], v[168:171], v[32:47]
	v_mfma_f32_32x32x16_bf16 v[64:79], v[174:177], v[128:131], v[64:79]
	v_cvt_pk_bf16_f32 v174, v120, v121
	v_cvt_pk_bf16_f32 v175, v122, v123
	s_waitcnt lgkmcnt(0)
	v_mfma_f32_32x32x16_bf16 v[80:95], v[112:115], v[136:139], v[80:95]
	v_exp_f32_e32 v112, v124
	v_exp_f32_e32 v113, v125
	v_exp_f32_e32 v114, v126
	v_exp_f32_e32 v115, v127
	v_cvt_pk_bf16_f32 v176, v112, v113
	v_cvt_pk_bf16_f32 v177, v114, v115
	v_mfma_f32_32x32x16_bf16 v[64:79], v[180:183], v[140:143], v[64:79]
	ds_read_b128 v[112:115], v206 offset:28672
	ds_read_b128 v[120:123], v206 offset:32768
	s_waitcnt lgkmcnt(0)
	v_mfma_f32_32x32x16_bf16 v[0:15], v[120:123], v[192:195], v[0:15]
	ds_read_b128 v[124:127], v205 offset:28672
	ds_read_b128 v[180:183], v205 offset:32768
	v_exp_f32_e32 v121, v96
	v_exp_f32_e32 v96, v97
	v_exp_f32_e32 v97, v98
	v_pk_add_f32 v[122:123], v[162:163], v[218:219]
	v_exp_f32_e32 v120, v99
	v_pk_add_f32 v[98:99], v[156:157], v[216:217]
	v_mfma_f32_32x32x16_bf16 v[16:31], v[112:115], v[192:195], v[16:31]
	v_add_f32_e64 v122, v222, v122
	v_add_f32_e64 v123, v223, v123
	v_add_f32_e64 v98, v220, v98
	v_add_f32_e64 v99, v221, v99
	v_exp_f32_e32 v163, v100
	v_exp_f32_e32 v184, v101
	v_exp_f32_e32 v185, v102
	v_exp_f32_e32 v162, v103
	v_pk_add_f32 v[122:123], v[226:227], v[122:123]
	v_pk_add_f32 v[98:99], v[224:225], v[98:99]
	v_pk_add_f32 v[122:123], v[230:231], v[122:123]
	v_pk_add_f32 v[98:99], v[228:229], v[98:99]
	v_pk_add_f32 v[168:169], v[122:123], v[96:97]
	v_pk_add_f32 v[156:157], v[98:99], v[120:121]
	v_cvt_pk_bf16_f32 v96, v121, v96
	v_cvt_pk_bf16_f32 v97, v97, v120
	v_cvt_pk_bf16_f32 v98, v163, v184
	v_cvt_pk_bf16_f32 v99, v185, v162
	s_waitcnt lgkmcnt(0)
	v_mfma_f32_32x32x16_bf16 v[0:15], v[180:183], v[174:177], v[0:15]
	ds_read_b128 v[100:103], v200 offset:28672
	ds_read_b128 v[180:183], v200 offset:32768
	v_exp_f32_e32 v171, v104
	v_exp_f32_e32 v188, v105
	v_exp_f32_e32 v189, v106
	v_exp_f32_e32 v170, v107
	v_exp_f32_e32 v187, v108
	v_exp_f32_e32 v190, v109
	v_mfma_f32_32x32x16_bf16 v[64:79], v[116:119], v[136:139], v[64:79]
	v_exp_f32_e32 v191, v110
	v_exp_f32_e32 v186, v111
	v_cvt_pk_bf16_f32 v104, v171, v188
	v_cvt_pk_bf16_f32 v105, v189, v170
	v_cvt_pk_bf16_f32 v106, v187, v190
	v_cvt_pk_bf16_f32 v107, v191, v186
	v_mfma_f32_32x32x16_bf16 v[16:31], v[124:127], v[174:177], v[16:31]
	s_waitcnt lgkmcnt(0)
	v_mfma_f32_32x32x16_bf16 v[16:31], v[100:103], v[96:99], v[16:31]
	ds_read_b128 v[108:111], v151 offset:28672
	ds_read_b128 v[218:221], v151 offset:32768
	s_waitcnt lgkmcnt(0)
	v_mfma_f32_32x32x16_bf16 v[16:31], v[108:111], v[104:107], v[16:31]
	s_waitcnt vmcnt(2)
	s_mov_b32 m0, s4
	s_waitcnt lgkmcnt(0)
	s_barrier
	global_load_lds_dwordx4 v244, s[34:35]
	s_mov_b32 m0, s5
	s_add_i32 s11, 0, 0x10000
	global_load_lds_dwordx4 v245, s[42:43]
	v_add_u32_e32 v215, s11, v207
	ds_read_b128 v[100:103], v201 offset:61440
	ds_read_b128 v[222:225], v215
	v_mfma_f32_32x32x16_bf16 v[0:15], v[180:183], v[96:99], v[0:15]
	v_add_u32_e32 v216, s11, v208
	ds_read_b128 v[96:99], v202 offset:61440
	ds_read_b128 v[180:183], v216
	v_exp_f32_e32 v226, v80
	v_exp_f32_e32 v227, v81
	v_exp_f32_e32 v228, v82
	v_exp_f32_e32 v229, v83
	v_mfma_f32_32x32x16_bf16 v[32:47], v[144:147], v[192:195], v[32:47]
	v_mfma_f32_32x32x16_bf16 v[0:15], v[218:221], v[104:107], v[0:15]
	s_waitcnt lgkmcnt(0)
	v_mfma_f32_32x32x16_bf16 v[112:127], v[100:103], v[132:135], v[48:63]
	ds_read_b128 v[80:83], v204 offset:61440
	v_add_u32_e32 v217, s11, v209
	ds_read_b128 v[192:195], v217
	v_exp_f32_e32 v84, v84
	v_exp_f32_e32 v85, v85
	v_exp_f32_e32 v86, v86
	v_exp_f32_e32 v87, v87
	v_cvt_pk_bf16_f32 v220, v226, v227
	v_mfma_f32_32x32x16_bf16 v[112:127], v[96:99], v[128:131], v[112:127]
	v_cvt_pk_bf16_f32 v221, v228, v229
	v_mfma_f32_32x32x16_bf16 v[96:111], v[222:225], v[132:135], v[48:63]
	v_cvt_pk_bf16_f32 v222, v84, v85
	v_cvt_pk_bf16_f32 v223, v86, v87
	v_mfma_f32_32x32x16_bf16 v[32:47], v[144:147], v[174:177], v[32:47]
	v_add_u32_e32 v218, s11, v210
	v_exp_f32_e32 v88, v88
	v_exp_f32_e32 v89, v89
	v_exp_f32_e32 v90, v90
	v_exp_f32_e32 v91, v91
	s_waitcnt lgkmcnt(0)
	v_mfma_f32_32x32x16_bf16 v[112:127], v[80:83], v[140:143], v[112:127]
	ds_read_b128 v[80:83], v203 offset:61440
	ds_read_b128 v[84:87], v218
	s_waitcnt lgkmcnt(0)
	v_mfma_f32_32x32x16_bf16 v[112:127], v[80:83], v[136:139], v[112:127]
	v_exp_f32_e32 v80, v92
	v_exp_f32_e32 v81, v93
	v_exp_f32_e32 v82, v94
	v_exp_f32_e32 v83, v95
	v_cvt_pk_bf16_f32 v174, v88, v89
	v_cvt_pk_bf16_f32 v175, v90, v91
	v_cvt_pk_bf16_f32 v176, v80, v81
	v_mfma_f32_32x32x16_bf16 v[96:111], v[180:183], v[128:131], v[96:111]
	v_cvt_pk_bf16_f32 v177, v82, v83
	ds_read_b128 v[80:83], v206 offset:49152
	ds_read_b128 v[88:91], v206 offset:53248
	v_mfma_f32_32x32x16_bf16 v[96:111], v[192:195], v[140:143], v[96:111]
	s_waitcnt lgkmcnt(0)
	v_mfma_f32_32x32x16_bf16 v[0:15], v[88:91], v[220:223], v[0:15]
	ds_read_b128 v[92:95], v205 offset:49152
	ds_read_b128 v[180:183], v205 offset:53248
	v_exp_f32_e32 v193, v64
	v_exp_f32_e32 v194, v65
	v_exp_f32_e32 v195, v66
	v_exp_f32_e32 v192, v67
	v_exp_f32_e32 v229, v68
	v_exp_f32_e32 v230, v69
	v_mfma_f32_32x32x16_bf16 v[16:31], v[80:83], v[220:223], v[16:31]
	v_exp_f32_e32 v231, v70
	v_exp_f32_e32 v228, v71
	v_cvt_pk_bf16_f32 v64, v193, v194
	v_cvt_pk_bf16_f32 v65, v195, v192
	v_cvt_pk_bf16_f32 v66, v229, v230
	v_cvt_pk_bf16_f32 v67, v231, v228
	s_waitcnt lgkmcnt(0)
	v_mfma_f32_32x32x16_bf16 v[0:15], v[180:183], v[174:177], v[0:15]
	ds_read_b128 v[68:71], v200 offset:49152
	ds_read_b128 v[180:183], v200 offset:53248
	v_exp_f32_e32 v233, v72
	v_exp_f32_e32 v234, v73
	v_exp_f32_e32 v235, v74
	v_exp_f32_e32 v232, v75
	v_exp_f32_e32 v237, v76
	v_exp_f32_e32 v238, v77
	v_mfma_f32_32x32x16_bf16 v[16:31], v[92:95], v[174:177], v[16:31]
	v_exp_f32_e32 v239, v78
	v_exp_f32_e32 v236, v79
	v_cvt_pk_bf16_f32 v72, v233, v234
	v_cvt_pk_bf16_f32 v73, v235, v232
	v_cvt_pk_bf16_f32 v74, v237, v238
	v_cvt_pk_bf16_f32 v75, v239, v236
	v_mfma_f32_32x32x16_bf16 v[96:111], v[84:87], v[136:139], v[96:111]
	s_waitcnt lgkmcnt(0)
	v_mfma_f32_32x32x16_bf16 v[16:31], v[68:71], v[64:67], v[16:31]
	ds_read_b128 v[76:79], v151 offset:49152
	ds_read_b128 v[224:227], v151 offset:53248
	s_waitcnt lgkmcnt(0)
	v_mfma_f32_32x32x16_bf16 v[16:31], v[76:79], v[72:75], v[16:31]
	s_waitcnt vmcnt(2)
	s_mov_b32 m0, s6
	s_waitcnt lgkmcnt(0)
	s_barrier
; template <int TYPE, bool FIXREF>
; DI void attn_dense_unit(const Params& p, int layer, int head, int qb, char* lds, float bref) {
;     ...
;   for (int t = 0; t < NT - 4; t += 4) {
;     STEP(sA0, sA1, sB0, sB1, t, true, true, R0, R1, R3);
;     STEP(sB0, sB1, sA0, sA1, t + 1, true, true, R1, R2, R0);
;     STEP(sA0, sA1, sB0, sB1, t + 2, true, true, R2, R3, R1);
;     STEP(sB0, sB1, sA0, sA1, t + 3, true, true, R3, R0, R2);
;   }
	global_load_lds_dwordx4 v244, s[44:45]
	s_mov_b32 m0, s7
	s_nop 0
	global_load_lds_dwordx4 v245, s[46:47]
	ds_read_b128 v[68:71], v201
	ds_read_b128 v[164:167], v201 offset:4096
	v_mfma_f32_32x32x16_bf16 v[0:15], v[180:183], v[64:67], v[0:15]
	ds_read_b128 v[64:67], v202
	ds_read_b128 v[180:183], v202 offset:4096
	s_waitcnt lgkmcnt(0)
	v_mfma_f32_32x32x16_bf16 v[80:95], v[68:71], v[132:135], v[48:63]
	v_exp_f32_e32 v68, v112
	v_exp_f32_e32 v69, v113
	v_exp_f32_e32 v70, v114
	v_exp_f32_e32 v71, v115
	v_mfma_f32_32x32x16_bf16 v[32:47], v[144:147], v[220:223], v[32:47]
	v_mfma_f32_32x32x16_bf16 v[0:15], v[224:227], v[72:75], v[0:15]
	v_mfma_f32_32x32x16_bf16 v[80:95], v[64:67], v[128:131], v[80:95]
	v_exp_f32_e32 v64, v116
	v_exp_f32_e32 v65, v117
	v_exp_f32_e32 v66, v118
	v_exp_f32_e32 v67, v119
	v_cvt_pk_bf16_f32 v116, v68, v69
	v_cvt_pk_bf16_f32 v117, v70, v71
	v_cvt_pk_bf16_f32 v118, v64, v65
	v_cvt_pk_bf16_f32 v119, v66, v67
	v_mfma_f32_32x32x16_bf16 v[64:79], v[164:167], v[132:135], v[48:63]
	ds_read_b128 v[112:115], v204
	ds_read_b128 v[220:223], v204 offset:4096
	s_waitcnt lgkmcnt(0)
	v_mfma_f32_32x32x16_bf16 v[80:95], v[112:115], v[140:143], v[80:95]
	ds_read_b128 v[112:115], v203
	ds_read_b128 v[224:227], v203 offset:4096
	v_exp_f32_e32 v120, v120
	v_exp_f32_e32 v121, v121
	v_exp_f32_e32 v122, v122
	v_exp_f32_e32 v123, v123
	v_mfma_f32_32x32x16_bf16 v[32:47], v[144:147], v[174:177], v[32:47]
	v_mfma_f32_32x32x16_bf16 v[64:79], v[180:183], v[128:131], v[64:79]
	v_add_u32_e32 v166, 0, v211
	v_add_u32_e32 v167, s11, v211
	s_waitcnt lgkmcnt(0)
	v_mfma_f32_32x32x16_bf16 v[80:95], v[112:115], v[136:139], v[80:95]
	v_exp_f32_e32 v114, v124
	v_exp_f32_e32 v115, v125
	v_exp_f32_e32 v124, v126
	v_exp_f32_e32 v125, v127
	v_cvt_pk_bf16_f32 v112, v120, v121
	v_cvt_pk_bf16_f32 v113, v122, v123
	v_cvt_pk_bf16_f32 v114, v114, v115
	v_mfma_f32_32x32x16_bf16 v[64:79], v[220:223], v[140:143], v[64:79]
	v_cvt_pk_bf16_f32 v115, v124, v125
	ds_read_b128 v[120:123], v166 offset:61440
	ds_read_b128 v[124:127], v167
	s_waitcnt lgkmcnt(0)
	v_mfma_f32_32x32x16_bf16 v[0:15], v[124:127], v[116:119], v[0:15]
	v_add_u32_e32 v164, 0, v212
	v_add_u32_e32 v165, s11, v212
	ds_read_b128 v[174:177], v164 offset:61440
	ds_read_b128 v[180:183], v165
	v_exp_f32_e32 v127, v96
	v_exp_f32_e32 v222, v97
	v_exp_f32_e32 v223, v98
	v_mfma_f32_32x32x16_bf16 v[16:31], v[120:123], v[116:119], v[16:31]
	v_exp_f32_e32 v126, v99
	v_exp_f32_e32 v241, v100
	v_exp_f32_e32 v242, v101
	v_exp_f32_e32 v243, v102
	v_exp_f32_e32 v240, v103
	v_cvt_pk_bf16_f32 v96, v127, v222
	v_cvt_pk_bf16_f32 v97, v223, v126
	v_cvt_pk_bf16_f32 v98, v241, v242
	v_cvt_pk_bf16_f32 v99, v243, v240
	v_mfma_f32_32x32x16_bf16 v[32:47], v[144:147], v[116:119], v[32:47]
	v_exp_f32_e32 v125, v104
	v_exp_f32_e32 v104, v105
	v_exp_f32_e32 v105, v106
	v_exp_f32_e32 v124, v107
	v_pk_add_f32 v[106:107], v[162:163], v[156:157]
	v_pk_add_f32 v[168:169], v[184:185], v[168:169]
	v_pk_add_f32 v[106:107], v[170:171], v[106:107]
	v_pk_add_f32 v[168:169], v[188:189], v[168:169]
	v_pk_add_f32 v[106:107], v[186:187], v[106:107]
	v_pk_add_f32 v[168:169], v[190:191], v[168:169]
	v_pk_add_f32 v[106:107], v[106:107], v[192:193]
	s_waitcnt lgkmcnt(0)
	v_mfma_f32_32x32x16_bf16 v[0:15], v[180:183], v[112:115], v[0:15]
	v_add_f32_e64 v168, v168, v194
	v_add_f32_e64 v169, v169, v195
	v_add_f32_e64 v106, v228, v106
	v_add_f32_e64 v107, v229, v107
	v_add_f32_e64 v168, v230, v168
	v_add_f32_e64 v169, v231, v169
	v_pk_add_f32 v[106:107], v[232:233], v[106:107]
	v_pk_add_f32 v[168:169], v[234:235], v[168:169]
	v_pk_add_f32 v[106:107], v[236:237], v[106:107]
	v_add_u32_e32 v219, 0, v213
	v_mfma_f32_32x32x16_bf16 v[64:79], v[224:227], v[136:139], v[64:79]
	v_add_u32_e32 v220, s11, v213
	v_add_f32_e64 v168, v238, v168
	v_add_f32_e64 v169, v239, v169
	v_add_f32_e64 v106, v106, v126
	v_add_f32_e64 v107, v107, v127
	v_exp_f32_e32 v127, v108
	v_exp_f32_e32 v108, v109
	v_exp_f32_e32 v109, v110
	v_exp_f32_e32 v126, v111
	v_mfma_f32_32x32x16_bf16 v[16:31], v[174:177], v[112:115], v[16:31]
	ds_read_b128 v[100:103], v219 offset:61440
	ds_read_b128 v[120:123], v220
	v_add_f32_e64 v168, v168, v222
	v_add_f32_e64 v169, v169, v223
	v_add_f32_e64 v106, v240, v106
	v_add_f32_e64 v107, v241, v107
	v_pk_add_f32 v[168:169], v[242:243], v[168:169]
	v_pk_add_f32 v[106:107], v[124:125], v[106:107]
	v_pk_add_f32 v[168:169], v[104:105], v[168:169]
	v_mfma_f32_32x32x16_bf16 v[32:47], v[144:147], v[112:115], v[32:47]
	v_add_f32_e64 v162, v108, v168
	v_add_f32_e64 v163, v109, v169
	v_add_f32_e64 v156, v126, v106
	v_add_f32_e64 v157, v127, v107
	v_cvt_pk_bf16_f32 v104, v125, v104
	v_cvt_pk_bf16_f32 v105, v105, v124
	v_cvt_pk_bf16_f32 v106, v127, v108
	v_cvt_pk_bf16_f32 v107, v109, v126
	s_waitcnt lgkmcnt(0)
	v_mfma_f32_32x32x16_bf16 v[16:31], v[100:103], v[96:99], v[16:31]
	v_add_u32_e32 v168, 0, v214
	v_add_u32_e32 v169, s11, v214
	ds_read_b128 v[100:103], v168 offset:61440
	ds_read_b128 v[108:111], v169
	v_mfma_f32_32x32x16_bf16 v[0:15], v[120:123], v[96:99], v[0:15]
	s_waitcnt lgkmcnt(0)
	v_mfma_f32_32x32x16_bf16 v[16:31], v[100:103], v[104:107], v[16:31]
	v_mfma_f32_32x32x16_bf16 v[0:15], v[108:111], v[104:107], v[0:15]
	s_waitcnt vmcnt(2)
	s_waitcnt lgkmcnt(0)
	s_barrier
	s_add_u32 s12, s12, s66
	s_addc_u32 s13, s13, s67
	s_add_u32 s16, s16, s66
	s_addc_u32 s17, s17, s67
	s_add_u32 s34, s34, s66
	s_addc_u32 s35, s35, s67
	s_add_u32 s44, s44, s66
	s_addc_u32 s45, s45, s67
	s_add_u32 s14, s14, s64
	s_addc_u32 s15, s15, s65
	s_add_u32 s18, s18, s64
	s_addc_u32 s19, s19, s65
	s_add_u32 s42, s42, s64
	s_addc_u32 s43, s43, s65
	s_add_u32 s46, s46, s64
	s_addc_u32 s47, s47, s65
	s_add_i32 s9, s9, 4
	s_cmpk_lt_u32 s9, 0xf8
	s_cbranch_scc1 .LBB0_541
; template <int TYPE, bool FIXREF>
; DI void attn_dense_unit(const Params& p, int layer, int head, int qb, char* lds, float bref) {
;     ...
;   STEP(sA0, sA1, sB0, sB1, NT - 4, true, true, R0, R1, R3);
;   STEP(sB0, sB1, sA0, sA1, NT - 3, true, false, R1, R2, R0);
	s_mov_b64 s[0:1], 0xef10000
	s_mov_b32 m0, s10
	v_lshl_add_u64 v[96:97], v[154:155], 0, s[0:1]
	s_mov_b64 s[0:1], 0x7f80
	global_load_lds_dwordx4 v[96:97], off
	v_lshl_add_u64 v[96:97], v[152:153], 0, s[0:1]
	s_mov_b32 m0, s8
	s_mov_b64 s[88:89], 0x17618300
	global_load_lds_dwordx4 v[96:97], off
	ds_read_b128 v[96:99], v201 offset:20480
	ds_read_b128 v[144:147], v201 offset:24576
	s_mov_b64 s[62:63], 0x33ba200
	ds_read_b128 v[100:103], v202 offset:20480
	ds_read_b128 v[152:155], v202 offset:24576
	v_exp_f32_e32 v170, v80
	v_exp_f32_e32 v171, v81
	v_exp_f32_e32 v172, v82
	v_exp_f32_e32 v175, v83
	s_waitcnt lgkmcnt(0)
	v_mfma_f32_32x32x16_bf16 v[112:127], v[96:99], v[132:135], v[48:63]
	ds_read_b128 v[80:83], v204 offset:20480
	ds_read_b128 v[158:161], v204 offset:24576
	v_exp_f32_e32 v84, v84
	v_exp_f32_e32 v85, v85
	v_exp_f32_e32 v86, v86
	v_exp_f32_e32 v87, v87
	v_mfma_f32_32x32x16_bf16 v[112:127], v[100:103], v[128:131], v[112:127]
	v_cvt_pk_bf16_f32 v174, v170, v171
	v_cvt_pk_bf16_f32 v175, v172, v175
	v_cvt_pk_bf16_f32 v176, v84, v85
	v_cvt_pk_bf16_f32 v177, v86, v87
	v_mfma_f32_32x32x16_bf16 v[96:111], v[144:147], v[132:135], v[48:63]
	ds_read_b128 v[84:87], v203 offset:20480
	ds_read_b128 v[144:147], v203 offset:24576
	s_waitcnt lgkmcnt(0)
	v_mfma_f32_32x32x16_bf16 v[112:127], v[80:83], v[140:143], v[112:127]
	v_exp_f32_e32 v80, v88
	v_exp_f32_e32 v81, v89
	v_exp_f32_e32 v82, v90
	v_exp_f32_e32 v83, v91
	v_mfma_f32_32x32x16_bf16 v[112:127], v[84:87], v[136:139], v[112:127]
	v_exp_f32_e32 v84, v92
	v_exp_f32_e32 v85, v93
	v_exp_f32_e32 v86, v94
	v_exp_f32_e32 v87, v95
	v_cvt_pk_bf16_f32 v180, v80, v81
	v_cvt_pk_bf16_f32 v181, v82, v83
	v_cvt_pk_bf16_f32 v182, v84, v85
	v_mfma_f32_32x32x16_bf16 v[96:111], v[152:155], v[128:131], v[96:111]
	v_cvt_pk_bf16_f32 v183, v86, v87
	ds_read_b128 v[80:83], v206 offset:8192
	ds_read_b128 v[84:87], v206 offset:12288
	v_mfma_f32_32x32x16_bf16 v[96:111], v[158:161], v[140:143], v[96:111]
	s_waitcnt lgkmcnt(0)
	v_mfma_f32_32x32x16_bf16 v[0:15], v[84:87], v[174:177], v[0:15]
	ds_read_b128 v[88:91], v205 offset:8192
	ds_read_b128 v[92:95], v205 offset:12288
	v_exp_f32_e32 v153, v64
	v_exp_f32_e32 v171, v65
	v_exp_f32_e32 v184, v66
	v_exp_f32_e32 v152, v67
	v_exp_f32_e32 v170, v68
	v_exp_f32_e32 v172, v69
	v_exp_f32_e32 v186, v70
	v_exp_f32_e32 v154, v71
	v_mfma_f32_32x32x16_bf16 v[16:31], v[80:83], v[174:177], v[16:31]
	v_cvt_pk_bf16_f32 v64, v153, v171
	v_cvt_pk_bf16_f32 v65, v184, v152
	v_cvt_pk_bf16_f32 v66, v170, v172
	v_cvt_pk_bf16_f32 v67, v186, v154
	s_waitcnt lgkmcnt(0)
	v_mfma_f32_32x32x16_bf16 v[0:15], v[92:95], v[180:183], v[0:15]
	ds_read_b128 v[68:71], v200 offset:8192
	ds_read_b128 v[190:193], v200 offset:12288
	v_exp_f32_e32 v185, v72
	v_exp_f32_e32 v187, v73
	v_exp_f32_e32 v189, v74
	v_exp_f32_e32 v158, v75
	v_exp_f32_e32 v155, v76
	v_exp_f32_e32 v188, v77
	v_exp_f32_e32 v194, v78
	v_exp_f32_e32 v160, v79
	v_mfma_f32_32x32x16_bf16 v[96:111], v[144:147], v[136:139], v[96:111]
	v_cvt_pk_bf16_f32 v72, v185, v187
	v_cvt_pk_bf16_f32 v73, v189, v158
	v_cvt_pk_bf16_f32 v74, v155, v188
	v_cvt_pk_bf16_f32 v75, v194, v160
	v_mfma_f32_32x32x16_bf16 v[16:31], v[88:91], v[180:183], v[16:31]
	ds_read_b128 v[76:79], v151 offset:8192
	ds_read_b128 v[208:211], v151 offset:12288
	s_waitcnt lgkmcnt(0)
	v_mfma_f32_32x32x16_bf16 v[16:31], v[68:71], v[64:67], v[16:31]
	v_mfma_f32_32x32x16_bf16 v[16:31], v[76:79], v[72:75], v[16:31]
	s_waitcnt vmcnt(2)
	s_waitcnt lgkmcnt(0)
	s_barrier
	ds_read_b128 v[68:71], v201 offset:40960
	ds_read_b128 v[222:225], v201 offset:45056
	v_mfma_f32_32x32x16_bf16 v[0:15], v[190:193], v[64:67], v[0:15]
	v_mov_b64_e32 v[146:147], s[38:39]
	v_mov_b64_e32 v[144:145], s[36:37]
	v_exp_f32_e32 v159, v112
	v_exp_f32_e32 v161, v113
	v_exp_f32_e32 v195, v114
	v_exp_f32_e32 v207, v115
	v_mfma_f32_32x32x16_bf16 v[0:15], v[208:211], v[72:75], v[0:15]
	v_mfma_f32_32x32x16_bf16 v[32:47], v[144:147], v[174:177], v[32:47]
	ds_read_b128 v[64:67], v202 offset:40960
	ds_read_b128 v[174:177], v202 offset:45056
	s_waitcnt lgkmcnt(0)
	v_mfma_f32_32x32x16_bf16 v[80:95], v[68:71], v[132:135], v[48:63]
	ds_read_b128 v[112:115], v204 offset:40960
	ds_read_b128 v[190:193], v204 offset:45056
	v_exp_f32_e32 v116, v116
	v_exp_f32_e32 v117, v117
	v_exp_f32_e32 v118, v118
	v_exp_f32_e32 v119, v119
	v_mfma_f32_32x32x16_bf16 v[80:95], v[64:67], v[128:131], v[80:95]
	v_cvt_pk_bf16_f32 v208, v159, v161
	v_cvt_pk_bf16_f32 v209, v195, v207
	v_cvt_pk_bf16_f32 v210, v116, v117
	v_cvt_pk_bf16_f32 v211, v118, v119
	v_mfma_f32_32x32x16_bf16 v[64:79], v[222:225], v[132:135], v[48:63]
	s_waitcnt lgkmcnt(0)
	v_mfma_f32_32x32x16_bf16 v[80:95], v[112:115], v[140:143], v[80:95]
	ds_read_b128 v[112:115], v203 offset:40960
	ds_read_b128 v[222:225], v203 offset:45056
	v_exp_f32_e32 v116, v120
	v_exp_f32_e32 v117, v121
	v_exp_f32_e32 v118, v122
	v_exp_f32_e32 v119, v123
	v_mfma_f32_32x32x16_bf16 v[32:47], v[144:147], v[180:183], v[32:47]
	s_waitcnt lgkmcnt(0)
	v_mfma_f32_32x32x16_bf16 v[80:95], v[112:115], v[136:139], v[80:95]
	v_exp_f32_e32 v114, v126
	v_exp_f32_e32 v115, v127
	v_exp_f32_e32 v112, v124
	v_exp_f32_e32 v113, v125
	v_cvt_pk_bf16_f32 v120, v116, v117
	v_cvt_pk_bf16_f32 v123, v114, v115
	ds_read_b128 v[114:117], v206 offset:28672
	ds_read_b128 v[124:127], v206 offset:32768
	v_mfma_f32_32x32x16_bf16 v[64:79], v[174:177], v[128:131], v[64:79]
	v_cvt_pk_bf16_f32 v121, v118, v119
	v_cvt_pk_bf16_f32 v122, v112, v113
	v_mfma_f32_32x32x16_bf16 v[64:79], v[190:193], v[140:143], v[64:79]
	s_waitcnt lgkmcnt(0)
; template <int TYPE, bool FIXREF>
; DI void attn_dense_unit(const Params& p, int layer, int head, int qb, char* lds, float bref) {
;     ...
;   STEP(sB0, sB1, sA0, sA1, NT - 3, true, false, R1, R2, R0);
;   STEP(sA0, sA1, sB0, sB1, NT - 2, true, false, R2, R3, R1);
	v_mfma_f32_32x32x16_bf16 v[0:15], v[124:127], v[208:211], v[0:15]
	ds_read_b128 v[174:177], v205 offset:28672
	ds_read_b128 v[180:183], v205 offset:32768
	v_exp_f32_e32 v159, v96
	v_exp_f32_e32 v195, v97
	v_exp_f32_e32 v207, v98
	v_exp_f32_e32 v112, v99
	v_exp_f32_e32 v161, v100
	v_exp_f32_e32 v221, v101
	v_mfma_f32_32x32x16_bf16 v[16:31], v[114:117], v[208:211], v[16:31]
	v_exp_f32_e32 v226, v102
	v_exp_f32_e32 v114, v103
	v_cvt_pk_bf16_f32 v124, v159, v195
	v_cvt_pk_bf16_f32 v125, v207, v112
	v_cvt_pk_bf16_f32 v126, v161, v221
	v_cvt_pk_bf16_f32 v127, v226, v114
	s_waitcnt lgkmcnt(0)
	v_mfma_f32_32x32x16_bf16 v[0:15], v[180:183], v[120:123], v[0:15]
	ds_read_b128 v[96:99], v200 offset:28672
	ds_read_b128 v[180:183], v200 offset:32768
	v_exp_f32_e32 v113, v104
	v_exp_f32_e32 v227, v105
	v_exp_f32_e32 v228, v106
	v_exp_f32_e32 v116, v107
	v_exp_f32_e32 v115, v108
	v_exp_f32_e32 v229, v109
	v_exp_f32_e32 v230, v110
	v_exp_f32_e32 v118, v111
	v_mfma_f32_32x32x16_bf16 v[64:79], v[222:225], v[136:139], v[64:79]
	v_cvt_pk_bf16_f32 v190, v113, v227
	v_cvt_pk_bf16_f32 v191, v228, v116
	v_cvt_pk_bf16_f32 v192, v115, v229
	v_cvt_pk_bf16_f32 v193, v230, v118
	v_mfma_f32_32x32x16_bf16 v[16:31], v[174:177], v[120:123], v[16:31]
	ds_read_b128 v[100:103], v151 offset:28672
	ds_read_b128 v[174:177], v151 offset:32768
	s_waitcnt lgkmcnt(0)
	v_mfma_f32_32x32x16_bf16 v[16:31], v[96:99], v[124:127], v[16:31]
	v_mfma_f32_32x32x16_bf16 v[16:31], v[100:103], v[190:193], v[16:31]
	s_waitcnt vmcnt(0)
	s_waitcnt lgkmcnt(0)
	s_barrier
	ds_read_b128 v[222:225], v201 offset:61440
	ds_read_b128 v[212:215], v215
	v_mfma_f32_32x32x16_bf16 v[0:15], v[180:183], v[124:127], v[0:15]
	ds_read_b128 v[124:127], v202 offset:61440
	ds_read_b128 v[180:183], v216
	v_exp_f32_e32 v117, v80
	v_exp_f32_e32 v119, v81
	v_exp_f32_e32 v201, v82
	v_exp_f32_e32 v202, v83
	v_mfma_f32_32x32x16_bf16 v[0:15], v[174:177], v[190:193], v[0:15]
	s_waitcnt lgkmcnt(0)
	v_mfma_f32_32x32x16_bf16 v[96:111], v[222:225], v[132:135], v[48:63]
	v_mfma_f32_32x32x16_bf16 v[32:47], v[144:147], v[208:211], v[32:47]
	ds_read_b128 v[80:83], v204 offset:61440
	ds_read_b128 v[174:177], v217
	v_mfma_f32_32x32x16_bf16 v[96:111], v[124:127], v[128:131], v[96:111]
	v_exp_f32_e32 v124, v84
	v_exp_f32_e32 v125, v85
	v_exp_f32_e32 v126, v86
	v_exp_f32_e32 v87, v87
	v_cvt_pk_bf16_f32 v84, v117, v119
	v_cvt_pk_bf16_f32 v85, v201, v202
	v_cvt_pk_bf16_f32 v86, v124, v125
	v_cvt_pk_bf16_f32 v87, v126, v87
	v_mfma_f32_32x32x16_bf16 v[48:63], v[212:215], v[132:135], v[48:63]
	s_waitcnt lgkmcnt(0)
	v_mfma_f32_32x32x16_bf16 v[96:111], v[80:83], v[140:143], v[96:111]
	ds_read_b128 v[80:83], v203 offset:61440
	ds_read_b128 v[124:127], v218
	v_exp_f32_e32 v88, v88
	v_exp_f32_e32 v89, v89
	v_exp_f32_e32 v90, v90
	v_exp_f32_e32 v91, v91
	v_mfma_f32_32x32x16_bf16 v[32:47], v[144:147], v[120:123], v[32:47]
	s_waitcnt lgkmcnt(0)
	v_mfma_f32_32x32x16_bf16 v[96:111], v[80:83], v[136:139], v[96:111]
	v_exp_f32_e32 v82, v92
	v_exp_f32_e32 v83, v93
	v_exp_f32_e32 v92, v94
	v_exp_f32_e32 v93, v95
	v_cvt_pk_bf16_f32 v80, v88, v89
	v_cvt_pk_bf16_f32 v81, v90, v91
	v_cvt_pk_bf16_f32 v82, v82, v83
	v_mfma_f32_32x32x16_bf16 v[48:63], v[180:183], v[128:131], v[48:63]
	v_cvt_pk_bf16_f32 v83, v92, v93
	ds_read_b128 v[88:91], v206 offset:49152
	ds_read_b128 v[92:95], v206 offset:53248
	v_mfma_f32_32x32x16_bf16 v[48:63], v[174:177], v[140:143], v[48:63]
	s_waitcnt lgkmcnt(0)
	v_mfma_f32_32x32x16_bf16 v[0:15], v[92:95], v[84:87], v[0:15]
	ds_read_b128 v[120:123], v205 offset:49152
	ds_read_b128 v[128:131], v205 offset:53248
	v_exp_f32_e32 v117, v64
	v_exp_f32_e32 v132, v65
	v_exp_f32_e32 v133, v66
	v_exp_f32_e32 v64, v67
	v_exp_f32_e32 v119, v68
	v_exp_f32_e32 v134, v69
	v_exp_f32_e32 v135, v70
	v_exp_f32_e32 v66, v71
	v_mfma_f32_32x32x16_bf16 v[16:31], v[88:91], v[84:87], v[16:31]
	v_cvt_pk_bf16_f32 v88, v117, v132
	v_cvt_pk_bf16_f32 v89, v133, v64
	v_cvt_pk_bf16_f32 v90, v119, v134
	v_cvt_pk_bf16_f32 v91, v135, v66
	s_waitcnt lgkmcnt(0)
	v_mfma_f32_32x32x16_bf16 v[0:15], v[128:131], v[80:83], v[0:15]
	ds_read_b128 v[92:95], v200 offset:49152
	ds_read_b128 v[128:131], v200 offset:53248
	v_exp_f32_e32 v65, v72
	v_exp_f32_e32 v140, v73
	v_exp_f32_e32 v141, v74
	v_exp_f32_e32 v68, v75
	v_exp_f32_e32 v67, v76
	v_exp_f32_e32 v70, v79
	v_mfma_f32_32x32x16_bf16 v[48:63], v[124:127], v[136:139], v[48:63]
	v_exp_f32_e32 v124, v77
	v_exp_f32_e32 v125, v78
	v_cvt_pk_bf16_f32 v72, v65, v140
	v_cvt_pk_bf16_f32 v73, v141, v68
	v_cvt_pk_bf16_f32 v74, v67, v124
	v_cvt_pk_bf16_f32 v75, v125, v70
	v_mfma_f32_32x32x16_bf16 v[16:31], v[120:123], v[80:83], v[16:31]
	ds_read_b128 v[76:79], v151 offset:49152
	ds_read_b128 v[120:123], v151 offset:53248
	s_waitcnt lgkmcnt(0)
	v_mfma_f32_32x32x16_bf16 v[16:31], v[92:95], v[88:91], v[16:31]
	v_mfma_f32_32x32x16_bf16 v[16:31], v[76:79], v[72:75], v[16:31]
	s_waitcnt vmcnt(0)
	s_waitcnt lgkmcnt(0)
	s_barrier
; template <int TYPE, bool FIXREF>
; DI void attn_dense_unit(const Params& p, int layer, int head, int qb, char* lds, float bref) {
;     ...
;   STEP(sB0, sB1, sA0, sA1, NT - 1, false, false, R3, R0, R2);
;   lsum += ls0 + ls1 + ls2;
	v_mfma_f32_32x32x16_bf16 v[0:15], v[128:131], v[88:91], v[0:15]
	v_exp_f32_e32 v69, v96
	v_exp_f32_e32 v71, v97
	v_exp_f32_e32 v77, v98
	v_exp_f32_e32 v78, v99
	v_mfma_f32_32x32x16_bf16 v[32:47], v[144:147], v[84:87], v[32:47]
	v_exp_f32_e32 v79, v100
	v_exp_f32_e32 v84, v101
	v_exp_f32_e32 v85, v102
	v_exp_f32_e32 v86, v103
	v_mfma_f32_32x32x16_bf16 v[32:47], v[144:147], v[80:83], v[32:47]
	v_cvt_pk_bf16_f32 v76, v69, v71
	v_cvt_pk_bf16_f32 v77, v77, v78
	v_cvt_pk_bf16_f32 v78, v79, v84
	v_cvt_pk_bf16_f32 v79, v85, v86
	v_exp_f32_e32 v69, v104
	v_exp_f32_e32 v71, v105
	v_exp_f32_e32 v80, v106
	v_exp_f32_e32 v81, v107
	v_exp_f32_e32 v82, v108
	v_exp_f32_e32 v83, v109
	v_exp_f32_e32 v84, v110
	v_exp_f32_e32 v85, v111
	v_mfma_f32_32x32x16_bf16 v[0:15], v[120:123], v[72:75], v[0:15]
	v_cvt_pk_bf16_f32 v73, v80, v81
	v_cvt_pk_bf16_f32 v74, v82, v83
	v_cvt_pk_bf16_f32 v75, v84, v85
	ds_read_b128 v[80:83], v166 offset:61440
	ds_read_b128 v[84:87], v167
	v_cvt_pk_bf16_f32 v72, v69, v71
	s_waitcnt lgkmcnt(0)
	v_mfma_f32_32x32x16_bf16 v[0:15], v[84:87], v[76:79], v[0:15]
	ds_read_b128 v[84:87], v164 offset:61440
	ds_read_b128 v[88:91], v165
	v_mfma_f32_32x32x16_bf16 v[16:31], v[80:83], v[76:79], v[16:31]
	v_exp_f32_e32 v69, v48
	v_add_f32_e32 v48, v163, v184
	v_add_f32_e32 v48, v186, v48
	v_add_f32_e32 v48, v189, v48
	v_add_f32_e32 v48, v194, v48
	v_add_f32_e32 v48, v48, v207
	v_add_f32_e32 v48, v226, v48
	v_add_f32_e32 v48, v228, v48
	v_add_f32_e32 v48, v230, v48
	s_waitcnt lgkmcnt(0)
	v_mfma_f32_32x32x16_bf16 v[0:15], v[88:91], v[72:75], v[0:15]
	v_exp_f32_e32 v88, v59
	v_exp_f32_e32 v59, v50
	v_add_f32_e32 v48, v48, v133
	v_exp_f32_e32 v71, v52
	v_exp_f32_e32 v52, v53
	v_exp_f32_e32 v53, v54
	v_add_f32_e32 v48, v135, v48
	v_mfma_f32_32x32x16_bf16 v[16:31], v[84:87], v[72:75], v[16:31]
	v_exp_f32_e32 v85, v56
	v_exp_f32_e32 v56, v58
	v_add_f32_e32 v48, v141, v48
	v_exp_f32_e32 v58, v62
	v_add_f32_e32 v48, v125, v48
	v_add_f32_e32 v48, v48, v59
	v_add_f32_e32 v48, v53, v48
	v_add_f32_e32 v48, v56, v48
	v_add_f32_e32 v91, v58, v48
	v_add_f32_e32 v48, v162, v171
	v_add_f32_e32 v48, v172, v48
	v_add_f32_e32 v48, v187, v48
	v_add_f32_e32 v48, v188, v48
	v_add_f32_e32 v48, v48, v195
	v_add_f32_e32 v48, v221, v48
	v_add_f32_e32 v48, v227, v48
	v_add_f32_e32 v48, v229, v48
	v_exp_f32_e32 v86, v55
	v_exp_f32_e32 v55, v49
	v_add_f32_e32 v48, v48, v132
	v_add_f32_e32 v48, v134, v48
	v_exp_f32_e32 v54, v57
	v_add_f32_e32 v48, v140, v48
	v_exp_f32_e32 v57, v61
	v_add_f32_e32 v48, v124, v48
	v_mfma_f32_32x32x16_bf16 v[32:47], v[144:147], v[76:79], v[32:47]
	v_add_f32_e32 v48, v48, v55
	v_add_f32_e32 v48, v52, v48
	v_add_f32_e32 v48, v54, v48
	ds_read_b128 v[80:83], v219 offset:61440
	ds_read_b128 v[92:95], v220
	v_add_f32_e32 v89, v57, v48
	v_add_f32_e32 v48, v157, v153
	v_exp_f32_e32 v84, v51
	v_exp_f32_e32 v90, v63
	v_exp_f32_e32 v87, v60
	v_add_f32_e32 v153, v170, v48
	v_mov_b32_e32 v157, v185
	v_pk_add_f32 v[48:49], v[156:157], v[152:153]
	v_mfma_f32_32x32x16_bf16 v[32:47], v[144:147], v[72:75], v[32:47]
	v_add_f32_e64 v48, v154, v48
	v_add_f32_e64 v49, v155, v49
	v_add_f32_e64 v48, v158, v48
	v_add_f32_e64 v49, v159, v49
	v_add_f32_e64 v50, v160, v48
	v_add_f32_e64 v51, v161, v49
	s_nop 5
	v_cvt_pk_bf16_f32 v34, v69, v55
	v_cvt_pk_bf16_f32 v35, v59, v84
	v_cvt_pk_bf16_f32 v36, v71, v52
	v_cvt_pk_bf16_f32 v37, v53, v86
	v_cvt_pk_bf16_f32 v38, v85, v54
	v_cvt_pk_bf16_f32 v39, v56, v88
	v_cvt_pk_bf16_f32 v40, v87, v57
	v_cvt_pk_bf16_f32 v41, v58, v90
	s_waitcnt lgkmcnt(0)
	v_mfma_f32_32x32x16_bf16 v[0:15], v[92:95], v[34:37], v[0:15]
	ds_read_b128 v[42:45], v168 offset:61440
	ds_read_b128 v[46:49], v169
	v_mfma_f32_32x32x16_bf16 v[16:31], v[80:83], v[34:37], v[16:31]
	s_waitcnt lgkmcnt(0)
	v_mfma_f32_32x32x16_bf16 v[0:15], v[46:49], v[38:41], v[0:15]
	v_mfma_f32_32x32x16_bf16 v[16:31], v[42:45], v[38:41], v[16:31]
	v_add_f32_e64 v34, v50, v112
	v_add_f32_e64 v35, v51, v113
	v_lshlrev_b32_e32 v172, 1, v150
	v_add_f32_e64 v34, v114, v34
	v_add_f32_e64 v35, v115, v35
	s_waitcnt vmcnt(0)
	s_waitcnt lgkmcnt(0)
	s_barrier
; DI unsigned pk2(float lo, float hi) { f32x2 v = {lo, hi}; bf16x2_t b = __builtin_convertvector(v, bf16x2_t); return __builtin_bit_cast(unsigned, b); }
; DI void store_o_wide(bf16_t* rowp, const f32x16& o, float inv, int h) {
; #pragma unroll
;   for (int pr = 0; pr < 2; ++pr) {
;     const int g = 2 * pr;
;     const unsigned ax = pk2(o[4 * g] * inv, o[4 * g + 1] * inv), ay = pk2(o[4 * g + 2] * inv, o[4 * g + 3] * inv);
;     const unsigned bx = pk2(o[4 * g + 4] * inv, o[4 * g + 5] * inv), by = pk2(o[4 * g + 6] * inv, o[4 * g + 7] * inv);
;     const auto sx = __builtin_amdgcn_permlane32_swap(ax, bx, false, false);
;     const auto sy = __builtin_amdgcn_permlane32_swap(ay, by, false, false);
;     const u32x4 w = {sx[0], sy[0], sx[1], sy[1]};
;     *(u32x4*)(rowp + 8 * (g + h)) = w;
;   }
; }
; template <int TYPE, bool FIXREF>
; DI void attn_dense_unit(const Params& p, int layer, int head, int qb, char* lds, float bref) {
;     ...
;   lsum += ls0 + ls1 + ls2;
;   const float l = (NONES > 0 ? la[0] : 0.f) + lsum + __shfl_xor(lsum, 32);
;     ...
;   const float inv = 1.0f / l;
;   bf16_t* op = O + (size_t)q * 512 + head * 64;
;   store_o_wide(op, o0, inv, h); store_o_wide(op + 32, o1, inv, h);
	v_pk_add_f32 v[34:35], v[116:117], v[34:35]
	s_nop 0
	v_pk_add_f32 v[34:35], v[118:119], v[34:35]
	s_nop 0
	v_pk_add_f32 v[34:35], v[34:35], v[64:65]
	s_nop 0
	v_pk_add_f32 v[34:35], v[66:67], v[34:35]
	s_nop 0
	v_pk_add_f32 v[34:35], v[68:69], v[34:35]
	s_nop 0
	v_pk_add_f32 v[34:35], v[70:71], v[34:35]
	s_nop 0
	v_pk_add_f32 v[34:35], v[34:35], v[84:85]
	s_nop 0
	v_pk_add_f32 v[34:35], v[86:87], v[34:35]
	s_nop 0
	v_pk_add_f32 v[34:35], v[88:89], v[34:35]
	s_nop 0
	v_pk_add_f32 v[34:35], v[90:91], v[34:35]
	s_nop 0
	v_add_f32_e32 v33, v34, v35
	ds_bpermute_b32 v34, v199, v33
	v_add_f32_e32 v32, v33, v32
	s_waitcnt lgkmcnt(0)
	v_add_f32_e32 v32, v32, v34
	v_div_scale_f32 v33, s[0:1], v32, v32, 1.0
	v_rcp_f32_e32 v34, v33
	v_readlane_b32 s0, v253, 13
	v_readlane_b32 s1, v253, 14
	v_fma_f32 v35, -v33, v34, 1.0
	v_fmac_f32_e32 v34, v35, v34
	v_div_scale_f32 v35, vcc, 1.0, v32, 1.0
	v_mul_f32_e32 v36, v35, v34
	v_fma_f32 v37, -v33, v36, v35
	v_fmac_f32_e32 v36, v37, v34
	v_fma_f32 v33, -v33, v36, v35
	v_div_fmas_f32 v33, v33, v34, v36
	v_div_fixup_f32 v32, v33, v32, 1.0
	v_lshlrev_b64 v[34:35], 10, v[148:149]
	v_pk_mul_f32 v[16:17], v[16:17], v[32:33] op_sel_hi:[1,0]
	v_pk_mul_f32 v[18:19], v[18:19], v[32:33] op_sel_hi:[1,0]
	v_pk_mul_f32 v[0:1], v[0:1], v[32:33] op_sel_hi:[1,0]
	v_pk_mul_f32 v[2:3], v[2:3], v[32:33] op_sel_hi:[1,0]
	v_lshl_add_u64 v[34:35], s[0:1], 0, v[34:35]
	v_cvt_pk_bf16_f32 v16, v16, v17
	v_cvt_pk_bf16_f32 v17, v18, v19
	v_pk_mul_f32 v[18:19], v[20:21], v[32:33] op_sel_hi:[1,0]
	v_pk_mul_f32 v[20:21], v[22:23], v[32:33] op_sel_hi:[1,0]
	v_cvt_pk_bf16_f32 v0, v0, v1
	v_cvt_pk_bf16_f32 v1, v2, v3
	v_pk_mul_f32 v[2:3], v[4:5], v[32:33] op_sel_hi:[1,0]
	v_pk_mul_f32 v[4:5], v[6:7], v[32:33] op_sel_hi:[1,0]
	v_lshl_add_u64 v[34:35], v[34:35], 0, s[68:69]
	v_cvt_pk_bf16_f32 v18, v18, v19
	v_cvt_pk_bf16_f32 v19, v20, v21
	v_cvt_pk_bf16_f32 v2, v2, v3
	v_cvt_pk_bf16_f32 v3, v4, v5
	v_permlane32_swap_b32_e32 v16, v18
	v_permlane32_swap_b32_e32 v17, v19
	v_lshl_add_u64 v[20:21], v[34:35], 0, v[172:173]
	v_permlane32_swap_b32_e32 v0, v2
	v_permlane32_swap_b32_e32 v1, v3
	global_store_dwordx4 v[20:21], v[16:19], off
	global_store_dwordx4 v[20:21], v[0:3], off offset:64
	v_pk_mul_f32 v[22:23], v[30:31], v[32:33] op_sel_hi:[1,0]
	v_pk_mul_f32 v[16:17], v[24:25], v[32:33] op_sel_hi:[1,0]
	v_pk_mul_f32 v[18:19], v[26:27], v[32:33] op_sel_hi:[1,0]
	v_pk_mul_f32 v[0:1], v[8:9], v[32:33] op_sel_hi:[1,0]
	v_pk_mul_f32 v[2:3], v[10:11], v[32:33] op_sel_hi:[1,0]
	v_cvt_pk_bf16_f32 v16, v16, v17
	v_cvt_pk_bf16_f32 v17, v18, v19
	v_pk_mul_f32 v[18:19], v[28:29], v[32:33] op_sel_hi:[1,0]
	v_cvt_pk_bf16_f32 v0, v0, v1
	v_cvt_pk_bf16_f32 v1, v2, v3
	v_pk_mul_f32 v[2:3], v[12:13], v[32:33] op_sel_hi:[1,0]
	v_pk_mul_f32 v[6:7], v[14:15], v[32:33] op_sel_hi:[1,0]
	v_cvt_pk_bf16_f32 v18, v18, v19
	v_cvt_pk_bf16_f32 v19, v22, v23
	v_cvt_pk_bf16_f32 v2, v2, v3
	v_cvt_pk_bf16_f32 v3, v6, v7
	v_permlane32_swap_b32_e32 v16, v18
	v_permlane32_swap_b32_e32 v17, v19
	v_lshl_add_u64 v[4:5], v[20:21], 0, 64
	v_permlane32_swap_b32_e32 v0, v2
	v_permlane32_swap_b32_e32 v1, v3
	global_store_dwordx4 v[20:21], v[16:19], off offset:32
